# P1 and P3 GEMM epilogues: the eight per-row rstd loads issued before the last K-iteration's LDS-DMA prefetches (on top of the P6 epilogue change)
# baseline (speedup 1.0000x reference)
.LBB0_338:
	ds_read_b128 v[150:153], v184
	ds_read_b128 v[154:157], v184 offset:1024
	ds_read_b128 v[158:161], v184 offset:2048
	ds_read_b128 v[162:165], v184 offset:3072
	ds_read_b128 v[166:169], v185
	ds_read_b128 v[170:173], v185 offset:1024
	ds_read_b128 v[174:177], v185 offset:2048
	ds_read_b128 v[178:181], v185 offset:3072
	s_add_u32 s16, s14, 0xfffc0080
	s_addc_u32 s17, s15, -1
	s_cmp_eq_u32 s85, 12
	s_cselect_b32 s19, s11, s17
	s_cselect_b32 s18, s13, s16
	s_cselect_b32 s17, s73, s84
	s_cselect_b32 s16, s75, s81
	v_lshl_add_u64 v[220:221], s[14:15], 0, v[142:143]
	s_add_i32 m0, s39, 0xc000
	ds_read_b128 v[188:191], v186
	ds_read_b128 v[192:195], v186 offset:1024
	ds_read_b128 v[196:199], v186 offset:2048
	ds_read_b128 v[200:203], v186 offset:3072
	ds_read_b128 v[204:207], v186 offset:4096
	ds_read_b128 v[208:211], v186 offset:5120
	ds_read_b128 v[212:215], v186 offset:6144
	ds_read_b128 v[216:219], v186 offset:7168
	global_load_lds_dwordx4 v[220:221], off
	v_lshl_add_u64 v[220:221], s[14:15], 0, v[144:145]
	s_add_i32 m0, s39, 0xe000
	s_nop 0
	global_load_lds_dwordx4 v[220:221], off
	s_waitcnt vmcnt(8)
	s_waitcnt lgkmcnt(0)
	s_barrier
	s_setprio 1
	s_waitcnt lgkmcnt(0)
	v_mfma_f32_16x16x32_bf16 v[126:129], v[150:153], v[188:191], v[126:129]
	v_mfma_f32_16x16x32_bf16 v[122:125], v[158:161], v[188:191], v[122:125]
	v_mfma_f32_16x16x32_bf16 v[110:113], v[150:153], v[196:199], v[110:113]
	v_mfma_f32_16x16x32_bf16 v[106:109], v[158:161], v[196:199], v[106:109]
	v_mfma_f32_16x16x32_bf16 v[94:97], v[150:153], v[204:207], v[94:97]
	v_mfma_f32_16x16x32_bf16 v[90:93], v[158:161], v[204:207], v[90:93]
	v_mfma_f32_16x16x32_bf16 v[78:81], v[150:153], v[212:215], v[78:81]
	v_mfma_f32_16x16x32_bf16 v[74:77], v[158:161], v[212:215], v[74:77]
	v_mfma_f32_16x16x32_bf16 v[126:129], v[154:157], v[192:195], v[126:129]
	v_mfma_f32_16x16x32_bf16 v[122:125], v[162:165], v[192:195], v[122:125]
	v_mfma_f32_16x16x32_bf16 v[110:113], v[154:157], v[200:203], v[110:113]
	v_mfma_f32_16x16x32_bf16 v[106:109], v[162:165], v[200:203], v[106:109]
	v_mfma_f32_16x16x32_bf16 v[94:97], v[154:157], v[208:211], v[94:97]
	v_mfma_f32_16x16x32_bf16 v[90:93], v[162:165], v[208:211], v[90:93]
	v_mfma_f32_16x16x32_bf16 v[78:81], v[154:157], v[216:219], v[78:81]
	v_mfma_f32_16x16x32_bf16 v[74:77], v[162:165], v[216:219], v[74:77]
	s_setprio 0
	s_setprio 1
	v_mfma_f32_16x16x32_bf16 v[118:121], v[166:169], v[188:191], v[118:121]
	v_mfma_f32_16x16x32_bf16 v[114:117], v[174:177], v[188:191], v[114:117]
	v_mfma_f32_16x16x32_bf16 v[102:105], v[166:169], v[196:199], v[102:105]
	v_mfma_f32_16x16x32_bf16 v[98:101], v[174:177], v[196:199], v[98:101]
	v_mfma_f32_16x16x32_bf16 v[86:89], v[166:169], v[204:207], v[86:89]
	v_mfma_f32_16x16x32_bf16 v[82:85], v[174:177], v[204:207], v[82:85]
	v_mfma_f32_16x16x32_bf16 v[70:73], v[166:169], v[212:215], v[70:73]
	v_mfma_f32_16x16x32_bf16 v[66:69], v[174:177], v[212:215], v[66:69]
	v_mfma_f32_16x16x32_bf16 v[118:121], v[170:173], v[192:195], v[118:121]
	v_mfma_f32_16x16x32_bf16 v[114:117], v[178:181], v[192:195], v[114:117]
	v_mfma_f32_16x16x32_bf16 v[102:105], v[170:173], v[200:203], v[102:105]
	v_mfma_f32_16x16x32_bf16 v[98:101], v[178:181], v[200:203], v[98:101]
	v_mfma_f32_16x16x32_bf16 v[86:89], v[170:173], v[208:211], v[86:89]
	v_mfma_f32_16x16x32_bf16 v[82:85], v[178:181], v[208:211], v[82:85]
	v_mfma_f32_16x16x32_bf16 v[70:73], v[170:173], v[216:219], v[70:73]
	v_mfma_f32_16x16x32_bf16 v[66:69], v[178:181], v[216:219], v[66:69]
	s_setprio 0
	s_barrier
	s_add_i32 s86, s54, s38
	v_lshl_add_u64 v[220:221], s[16:17], 0, v[132:133]
	s_mov_b32 m0, s86
	ds_read_b128 v[188:191], v186 offset:16384
	ds_read_b128 v[192:195], v186 offset:17408
	ds_read_b128 v[196:199], v186 offset:18432
	ds_read_b128 v[200:203], v186 offset:19456
	ds_read_b128 v[204:207], v186 offset:20480
	ds_read_b128 v[208:211], v186 offset:21504
	ds_read_b128 v[212:215], v186 offset:22528
	ds_read_b128 v[216:219], v186 offset:23552
	global_load_lds_dwordx4 v[220:221], off
	s_add_i32 m0, s86, 0x2000
	s_add_u32 s86, s16, 0x40000
	v_lshl_add_u64 v[222:223], s[16:17], 0, v[136:137]
	s_addc_u32 s87, s17, 0
	s_add_i32 s96, s55, s38
	global_load_lds_dwordx4 v[222:223], off
	v_lshl_add_u64 v[224:225], s[86:87], 0, v[132:133]
	s_mov_b32 m0, s96
	v_lshl_add_u64 v[226:227], s[18:19], 0, v[134:135]
	global_load_lds_dwordx4 v[224:225], off
	v_lshl_add_u64 v[224:225], s[86:87], 0, v[136:137]
	s_add_i32 m0, s96, 0x2000
	s_nop 0
	global_load_lds_dwordx4 v[224:225], off
	v_lshl_add_u64 v[224:225], s[18:19], 0, v[130:131]
	s_mov_b32 m0, s39
	s_nop 0
	global_load_lds_dwordx4 v[224:225], off
	s_mov_b32 m0, s40
	s_nop 0
	global_load_lds_dwordx4 v[226:227], off
	s_waitcnt vmcnt(8)
	s_waitcnt lgkmcnt(0)
	s_barrier
	s_setprio 1
	s_waitcnt lgkmcnt(0)
	v_mfma_f32_16x16x32_bf16 v[62:65], v[150:153], v[188:191], v[62:65]
	v_mfma_f32_16x16x32_bf16 v[58:61], v[158:161], v[188:191], v[58:61]
	v_mfma_f32_16x16x32_bf16 v[46:49], v[150:153], v[196:199], v[46:49]
	v_mfma_f32_16x16x32_bf16 v[42:45], v[158:161], v[196:199], v[42:45]
	v_mfma_f32_16x16x32_bf16 v[30:33], v[150:153], v[204:207], v[30:33]
	v_mfma_f32_16x16x32_bf16 v[26:29], v[158:161], v[204:207], v[26:29]
	v_mfma_f32_16x16x32_bf16 v[14:17], v[150:153], v[212:215], v[14:17]
	v_mfma_f32_16x16x32_bf16 v[10:13], v[158:161], v[212:215], v[10:13]
	v_mfma_f32_16x16x32_bf16 v[62:65], v[154:157], v[192:195], v[62:65]
	v_mfma_f32_16x16x32_bf16 v[58:61], v[162:165], v[192:195], v[58:61]
	v_mfma_f32_16x16x32_bf16 v[46:49], v[154:157], v[200:203], v[46:49]
	v_mfma_f32_16x16x32_bf16 v[42:45], v[162:165], v[200:203], v[42:45]
	v_mfma_f32_16x16x32_bf16 v[30:33], v[154:157], v[208:211], v[30:33]
	v_mfma_f32_16x16x32_bf16 v[26:29], v[162:165], v[208:211], v[26:29]
	v_mfma_f32_16x16x32_bf16 v[14:17], v[154:157], v[216:219], v[14:17]
	v_mfma_f32_16x16x32_bf16 v[10:13], v[162:165], v[216:219], v[10:13]
	s_setprio 0
	s_setprio 1
	v_mfma_f32_16x16x32_bf16 v[54:57], v[166:169], v[188:191], v[54:57]
	v_mfma_f32_16x16x32_bf16 v[50:53], v[174:177], v[188:191], v[50:53]
	v_mfma_f32_16x16x32_bf16 v[38:41], v[166:169], v[196:199], v[38:41]
	v_mfma_f32_16x16x32_bf16 v[34:37], v[174:177], v[196:199], v[34:37]
	v_mfma_f32_16x16x32_bf16 v[22:25], v[166:169], v[204:207], v[22:25]
	v_mfma_f32_16x16x32_bf16 v[18:21], v[174:177], v[204:207], v[18:21]
	v_mfma_f32_16x16x32_bf16 v[6:9], v[166:169], v[212:215], v[6:9]
	v_mfma_f32_16x16x32_bf16 v[2:5], v[174:177], v[212:215], v[2:5]
	v_mfma_f32_16x16x32_bf16 v[54:57], v[170:173], v[192:195], v[54:57]
	v_mfma_f32_16x16x32_bf16 v[50:53], v[178:181], v[192:195], v[50:53]
	v_mfma_f32_16x16x32_bf16 v[38:41], v[170:173], v[200:203], v[38:41]
	v_mfma_f32_16x16x32_bf16 v[34:37], v[178:181], v[200:203], v[34:37]
	v_mfma_f32_16x16x32_bf16 v[22:25], v[170:173], v[208:211], v[22:25]
	v_mfma_f32_16x16x32_bf16 v[18:21], v[178:181], v[208:211], v[18:21]
	v_mfma_f32_16x16x32_bf16 v[6:9], v[170:173], v[216:219], v[6:9]
	v_mfma_f32_16x16x32_bf16 v[2:5], v[178:181], v[216:219], v[2:5]
	s_setprio 0
	s_barrier
	s_add_i32 s86, 0, 0x18000
	v_add_u32_e32 v138, s86, v141
	s_add_i32 s87, 0, 0x1c000
	ds_read_b128 v[150:153], v138
	ds_read_b128 v[154:157], v138 offset:1024
	ds_read_b128 v[158:161], v138 offset:2048
	ds_read_b128 v[162:165], v138 offset:3072
	v_add_u32_e32 v138, s87, v141
	ds_read_b128 v[166:169], v138
	ds_read_b128 v[170:173], v138 offset:1024
	ds_read_b128 v[174:177], v138 offset:2048
	ds_read_b128 v[178:181], v138 offset:3072
	s_cmp_lg_u32 s85, 12
	s_cbranch_scc1 .Lg1_skip_ld
	v_or_b32_e32 v230, s47, v1
	v_lshl_add_u32 v230, s12, 8, v230
	v_lshlrev_b32_e32 v230, 2, v230
	global_load_dword v231, v230, s[64:65]
	global_load_dword v232, v230, s[64:65] offset:64
	global_load_dword v233, v230, s[64:65] offset:128
	global_load_dword v234, v230, s[64:65] offset:192
	global_load_dword v235, v230, s[64:65] offset:512
	global_load_dword v236, v230, s[64:65] offset:576
	global_load_dword v237, v230, s[64:65] offset:640
	global_load_dword v238, v230, s[64:65] offset:704
.Lg1_skip_ld:
	s_add_u32 s18, s18, 0x40000
	s_addc_u32 s19, s19, 0
	s_mov_b32 m0, s41
	v_lshl_add_u64 v[228:229], s[18:19], 0, v[130:131]
	ds_read_b128 v[188:191], v186 offset:32768
	ds_read_b128 v[192:195], v186 offset:33792
	ds_read_b128 v[196:199], v186 offset:34816
	ds_read_b128 v[200:203], v186 offset:35840
	ds_read_b128 v[204:207], v186 offset:36864
	ds_read_b128 v[208:211], v186 offset:37888
	ds_read_b128 v[212:215], v186 offset:38912
	ds_read_b128 v[216:219], v186 offset:39936
	global_load_lds_dwordx4 v[228:229], off
	v_lshl_add_u64 v[228:229], s[18:19], 0, v[134:135]
	s_mov_b32 m0, s42
	s_nop 0
	global_load_lds_dwordx4 v[228:229], off
	s_cmp_eq_u32 s85, 12
	s_cbranch_scc1 .Lg1_w1_last
	s_waitcnt vmcnt(8)
	s_branch .Lg1_w1_end
.Lg1_w1_last:
	s_waitcnt vmcnt(16)
.Lg1_w1_end:
	s_waitcnt lgkmcnt(0)
	s_barrier
	s_setprio 1
	s_waitcnt lgkmcnt(0)
	v_mfma_f32_16x16x32_bf16 v[126:129], v[150:153], v[188:191], v[126:129]
	v_mfma_f32_16x16x32_bf16 v[122:125], v[158:161], v[188:191], v[122:125]
	v_mfma_f32_16x16x32_bf16 v[110:113], v[150:153], v[196:199], v[110:113]
	v_mfma_f32_16x16x32_bf16 v[106:109], v[158:161], v[196:199], v[106:109]
	v_mfma_f32_16x16x32_bf16 v[94:97], v[150:153], v[204:207], v[94:97]
	v_mfma_f32_16x16x32_bf16 v[90:93], v[158:161], v[204:207], v[90:93]
	v_mfma_f32_16x16x32_bf16 v[78:81], v[150:153], v[212:215], v[78:81]
	v_mfma_f32_16x16x32_bf16 v[74:77], v[158:161], v[212:215], v[74:77]
	v_mfma_f32_16x16x32_bf16 v[126:129], v[154:157], v[192:195], v[126:129]
	v_mfma_f32_16x16x32_bf16 v[122:125], v[162:165], v[192:195], v[122:125]
	v_mfma_f32_16x16x32_bf16 v[110:113], v[154:157], v[200:203], v[110:113]
	v_mfma_f32_16x16x32_bf16 v[106:109], v[162:165], v[200:203], v[106:109]
	v_mfma_f32_16x16x32_bf16 v[94:97], v[154:157], v[208:211], v[94:97]
	v_mfma_f32_16x16x32_bf16 v[90:93], v[162:165], v[208:211], v[90:93]
	v_mfma_f32_16x16x32_bf16 v[78:81], v[154:157], v[216:219], v[78:81]
	v_mfma_f32_16x16x32_bf16 v[74:77], v[162:165], v[216:219], v[74:77]
	s_setprio 0
	s_setprio 1
	v_mfma_f32_16x16x32_bf16 v[118:121], v[166:169], v[188:191], v[118:121]
	v_mfma_f32_16x16x32_bf16 v[114:117], v[174:177], v[188:191], v[114:117]
	v_mfma_f32_16x16x32_bf16 v[102:105], v[166:169], v[196:199], v[102:105]
	v_mfma_f32_16x16x32_bf16 v[98:101], v[174:177], v[196:199], v[98:101]
	v_mfma_f32_16x16x32_bf16 v[86:89], v[166:169], v[204:207], v[86:89]
	v_mfma_f32_16x16x32_bf16 v[82:85], v[174:177], v[204:207], v[82:85]
	v_mfma_f32_16x16x32_bf16 v[70:73], v[166:169], v[212:215], v[70:73]
	v_mfma_f32_16x16x32_bf16 v[66:69], v[174:177], v[212:215], v[66:69]
	v_mfma_f32_16x16x32_bf16 v[118:121], v[170:173], v[192:195], v[118:121]
	v_mfma_f32_16x16x32_bf16 v[114:117], v[178:181], v[192:195], v[114:117]
	v_mfma_f32_16x16x32_bf16 v[102:105], v[170:173], v[200:203], v[102:105]
	v_mfma_f32_16x16x32_bf16 v[98:101], v[178:181], v[200:203], v[98:101]
	v_mfma_f32_16x16x32_bf16 v[86:89], v[170:173], v[208:211], v[86:89]
	v_mfma_f32_16x16x32_bf16 v[82:85], v[178:181], v[208:211], v[82:85]
	v_mfma_f32_16x16x32_bf16 v[70:73], v[170:173], v[216:219], v[70:73]
	v_mfma_f32_16x16x32_bf16 v[66:69], v[178:181], v[216:219], v[66:69]
	s_setprio 0
	s_barrier
	s_add_i32 s18, s86, s38
	v_lshl_add_u64 v[220:221], v[220:221], 0, s[36:37]
	s_mov_b32 m0, s18
	ds_read_b128 v[188:191], v186 offset:49152
	ds_read_b128 v[192:195], v186 offset:50176
	ds_read_b128 v[196:199], v186 offset:51200
	ds_read_b128 v[200:203], v186 offset:52224
	ds_read_b128 v[204:207], v186 offset:53248
	ds_read_b128 v[208:211], v186 offset:54272
	ds_read_b128 v[212:215], v186 offset:55296
	ds_read_b128 v[216:219], v186 offset:56320
	global_load_lds_dwordx4 v[220:221], off
	s_add_i32 m0, s18, 0x2000
	s_add_u32 s16, s16, 0x40080
	v_lshl_add_u64 v[220:221], v[222:223], 0, s[36:37]
	s_addc_u32 s17, s17, 0
	s_add_i32 s18, s87, s38
	global_load_lds_dwordx4 v[220:221], off
	v_lshl_add_u64 v[220:221], s[16:17], 0, v[132:133]
	s_mov_b32 m0, s18
	s_nop 0
	global_load_lds_dwordx4 v[220:221], off
	v_lshl_add_u64 v[220:221], s[16:17], 0, v[136:137]
	s_add_i32 m0, s18, 0x2000
	s_nop 0
	global_load_lds_dwordx4 v[220:221], off
	v_lshl_add_u64 v[220:221], v[224:225], 0, s[36:37]
	s_mov_b32 m0, s48
	s_nop 0
	global_load_lds_dwordx4 v[220:221], off
	v_lshl_add_u64 v[220:221], v[226:227], 0, s[36:37]
	s_mov_b32 m0, s49
	s_nop 0
	global_load_lds_dwordx4 v[220:221], off
	s_cmp_eq_u32 s85, 12
	s_cbranch_scc1 .Lg1_w2_last
	s_waitcnt vmcnt(8)
	s_branch .Lg1_w2_end

.Lg1_w2_end:
	s_waitcnt lgkmcnt(0)
	s_barrier
	s_setprio 1
	s_waitcnt lgkmcnt(0)
	v_mfma_f32_16x16x32_bf16 v[62:65], v[150:153], v[188:191], v[62:65]
	v_mfma_f32_16x16x32_bf16 v[58:61], v[158:161], v[188:191], v[58:61]
	v_mfma_f32_16x16x32_bf16 v[46:49], v[150:153], v[196:199], v[46:49]
	v_mfma_f32_16x16x32_bf16 v[42:45], v[158:161], v[196:199], v[42:45]
	v_mfma_f32_16x16x32_bf16 v[30:33], v[150:153], v[204:207], v[30:33]
	v_mfma_f32_16x16x32_bf16 v[26:29], v[158:161], v[204:207], v[26:29]
	v_mfma_f32_16x16x32_bf16 v[14:17], v[150:153], v[212:215], v[14:17]
	v_mfma_f32_16x16x32_bf16 v[10:13], v[158:161], v[212:215], v[10:13]
	v_mfma_f32_16x16x32_bf16 v[62:65], v[154:157], v[192:195], v[62:65]
	v_mfma_f32_16x16x32_bf16 v[58:61], v[162:165], v[192:195], v[58:61]
	v_mfma_f32_16x16x32_bf16 v[46:49], v[154:157], v[200:203], v[46:49]
	v_mfma_f32_16x16x32_bf16 v[42:45], v[162:165], v[200:203], v[42:45]
	v_mfma_f32_16x16x32_bf16 v[30:33], v[154:157], v[208:211], v[30:33]
	v_mfma_f32_16x16x32_bf16 v[26:29], v[162:165], v[208:211], v[26:29]
	v_mfma_f32_16x16x32_bf16 v[14:17], v[154:157], v[216:219], v[14:17]
	v_mfma_f32_16x16x32_bf16 v[10:13], v[162:165], v[216:219], v[10:13]
	s_setprio 0
	s_setprio 1
	v_mfma_f32_16x16x32_bf16 v[54:57], v[166:169], v[188:191], v[54:57]
	v_mfma_f32_16x16x32_bf16 v[50:53], v[174:177], v[188:191], v[50:53]
	v_mfma_f32_16x16x32_bf16 v[38:41], v[166:169], v[196:199], v[38:41]
	v_mfma_f32_16x16x32_bf16 v[34:37], v[174:177], v[196:199], v[34:37]
	v_mfma_f32_16x16x32_bf16 v[22:25], v[166:169], v[204:207], v[22:25]
	v_mfma_f32_16x16x32_bf16 v[18:21], v[174:177], v[204:207], v[18:21]
	v_mfma_f32_16x16x32_bf16 v[6:9], v[166:169], v[212:215], v[6:9]
	v_mfma_f32_16x16x32_bf16 v[2:5], v[174:177], v[212:215], v[2:5]
	v_mfma_f32_16x16x32_bf16 v[54:57], v[170:173], v[192:195], v[54:57]
	v_mfma_f32_16x16x32_bf16 v[50:53], v[178:181], v[192:195], v[50:53]
	v_mfma_f32_16x16x32_bf16 v[38:41], v[170:173], v[200:203], v[38:41]
	v_mfma_f32_16x16x32_bf16 v[34:37], v[178:181], v[200:203], v[34:37]
	v_mfma_f32_16x16x32_bf16 v[22:25], v[170:173], v[208:211], v[22:25]
	v_mfma_f32_16x16x32_bf16 v[18:21], v[178:181], v[208:211], v[18:21]
	v_mfma_f32_16x16x32_bf16 v[6:9], v[170:173], v[216:219], v[6:9]
	v_mfma_f32_16x16x32_bf16 v[2:5], v[178:181], v[216:219], v[2:5]
	s_setprio 0
	s_barrier
	s_add_i32 s85, s85, 2
	s_add_u32 s14, s14, 0x100
	s_addc_u32 s15, s15, 0
	s_add_u32 s81, s81, 0x100
	s_addc_u32 s84, s84, 0
	s_cmp_gt_u32 s85, 13
	s_cbranch_scc0 .LBB0_338
	s_and_b64 vcc, exec, s[52:53]
	s_cbranch_vccz .LBB0_341
	s_barrier
.LBB0_341:
	s_lshl_b32 s18, s12, 8
	s_add_i32 s18, s18, s47
	v_or_b32_e32 v152, s18, v1
	v_or_b32_e32 v174, 16, v152
	v_ashrrev_i32_e32 v153, 31, v152
	v_ashrrev_i32_e32 v175, 31, v174
	v_or_b32_e32 v170, 32, v152
	v_lshl_add_u64 v[150:151], v[152:153], 2, s[64:65]
	v_lshl_add_u64 v[154:155], v[174:175], 2, s[64:65]
	v_ashrrev_i32_e32 v171, 31, v170
	v_or_b32_e32 v166, 48, v152
	v_lshl_add_u64 v[154:155], v[170:171], 2, s[64:65]
	v_ashrrev_i32_e32 v167, 31, v166
	v_lshl_add_u64 v[154:155], v[166:167], 2, s[64:65]
	s_nop 0
	s_cmp_gt_i32 s10, 11
	s_cselect_b64 s[12:13], -1, 0
	s_cmp_lt_i32 s10, 12
	s_cselect_b64 s[86:87], -1, 0
	s_mov_b64 s[16:17], -1
	s_and_b64 vcc, exec, s[86:87]
	s_cbranch_vccz .LBB0_343
	v_cmp_gt_i32_e32 vcc, s44, v152
	s_or_b64 s[14:15], vcc, s[6:7]
	s_mov_b64 s[16:17], 0
.LBB0_343:
	s_waitcnt vmcnt(8)
	v_mov_b32_e32 v176, v231
	v_mov_b32_e32 v172, v232
	v_mov_b32_e32 v168, v233
	v_mov_b32_e32 v164, v234
	v_mov_b32_e32 v162, v235
	v_mov_b32_e32 v160, v236
	v_mov_b32_e32 v158, v237
	v_mov_b32_e32 v150, v238
	v_pk_mul_f32 v[128:129], v[128:129], v[176:177] op_sel_hi:[1,0]
	v_pk_mul_f32 v[126:127], v[126:127], v[176:177] op_sel_hi:[1,0]
	v_pk_mul_f32 v[124:125], v[124:125], v[176:177] op_sel_hi:[1,0]
	s_andn2_b64 vcc, exec, s[16:17]
	v_pk_mul_f32 v[122:123], v[122:123], v[176:177] op_sel_hi:[1,0]
	s_cbranch_vccnz .LBB0_345
	v_mul_f32_e32 v138, 0xbfb8aa3b, v126
	v_exp_f32_e32 v138, v138
	s_or_b64 s[14:15], s[14:15], exec
	v_add_f32_e32 v138, 1.0, v138
	v_rcp_f32_e32 v154, v138
	v_mul_f32_e32 v138, 0xbfb8aa3b, v122
	v_exp_f32_e32 v138, v138
	s_nop 0
	v_add_f32_e32 v138, 1.0, v138
	v_rcp_f32_e32 v156, v138
	v_mul_f32_e32 v138, 0xbfb8aa3b, v127
	v_exp_f32_e32 v138, v138
	s_nop 0
	v_add_f32_e32 v138, 1.0, v138
	v_rcp_f32_e32 v155, v138
	v_mul_f32_e32 v138, 0xbfb8aa3b, v123
	v_exp_f32_e32 v138, v138
	v_pk_mul_f32 v[126:127], v[126:127], v[154:155]
	v_add_f32_e32 v138, 1.0, v138
	v_rcp_f32_e32 v157, v138
	v_mul_f32_e32 v138, 0xbfb8aa3b, v128
	v_exp_f32_e32 v138, v138
	v_pk_mul_f32 v[122:123], v[122:123], v[156:157]
	v_add_f32_e32 v138, 1.0, v138
	v_rcp_f32_e32 v178, v138
	v_mul_f32_e32 v138, 0xbfb8aa3b, v124
	v_exp_f32_e32 v138, v138
	s_nop 0
	v_add_f32_e32 v138, 1.0, v138
	v_rcp_f32_e32 v180, v138
	v_mul_f32_e32 v138, 0xbfb8aa3b, v129
	v_exp_f32_e32 v138, v138
	s_nop 0
	v_add_f32_e32 v138, 1.0, v138
	v_rcp_f32_e32 v179, v138
	v_mul_f32_e32 v138, 0xbfb8aa3b, v125
	v_exp_f32_e32 v138, v138
	v_pk_mul_f32 v[128:129], v[128:129], v[178:179]
	v_add_f32_e32 v138, 1.0, v138
	v_rcp_f32_e32 v181, v138
	s_nop 0
	v_pk_mul_f32 v[124:125], v[124:125], v[180:181]

.LBB0_1296:
	ds_read_b128 v[162:165], v155
	ds_read_b128 v[166:169], v155 offset:1024
	ds_read_b128 v[170:173], v155 offset:2048
	ds_read_b128 v[174:177], v155 offset:3072
	ds_read_b128 v[178:181], v157
	ds_read_b128 v[182:185], v157 offset:1024
	ds_read_b128 v[186:189], v157 offset:2048
	ds_read_b128 v[190:193], v157 offset:3072
	s_add_u32 s24, s22, 0xfffc0080
	s_addc_u32 s25, s23, -1
	s_cmp_eq_u32 s47, 12
	s_cselect_b32 s27, s15, s25
	s_cselect_b32 s26, s43, s24
	s_cselect_b32 s25, s13, s46
	s_cselect_b32 s24, s44, s45
	v_lshl_add_u64 v[146:147], s[22:23], 0, v[138:139]
	s_add_i32 m0, s21, 0xc000
	ds_read_b128 v[194:197], v161
	ds_read_b128 v[198:201], v161 offset:1024
	ds_read_b128 v[202:205], v161 offset:2048
	ds_read_b128 v[206:209], v161 offset:3072
	ds_read_b128 v[210:213], v161 offset:4096
	ds_read_b128 v[214:217], v161 offset:5120
	ds_read_b128 v[218:221], v161 offset:6144
	ds_read_b128 v[222:225], v161 offset:7168
	global_load_lds_dwordx4 v[146:147], off
	v_lshl_add_u64 v[146:147], s[22:23], 0, v[140:141]
	s_add_i32 m0, s21, 0xe000
	s_nop 0
	global_load_lds_dwordx4 v[146:147], off
	s_waitcnt vmcnt(8)
	s_waitcnt lgkmcnt(0)
	s_barrier
	s_setprio 1
	s_waitcnt lgkmcnt(0)
	v_mfma_f32_16x16x32_bf16 v[126:129], v[162:165], v[194:197], v[126:129]
	v_mfma_f32_16x16x32_bf16 v[122:125], v[170:173], v[194:197], v[122:125]
	v_mfma_f32_16x16x32_bf16 v[110:113], v[162:165], v[202:205], v[110:113]
	v_mfma_f32_16x16x32_bf16 v[106:109], v[170:173], v[202:205], v[106:109]
	v_mfma_f32_16x16x32_bf16 v[94:97], v[162:165], v[210:213], v[94:97]
	v_mfma_f32_16x16x32_bf16 v[90:93], v[170:173], v[210:213], v[90:93]
	v_mfma_f32_16x16x32_bf16 v[78:81], v[162:165], v[218:221], v[78:81]
	v_mfma_f32_16x16x32_bf16 v[74:77], v[170:173], v[218:221], v[74:77]
	v_mfma_f32_16x16x32_bf16 v[126:129], v[166:169], v[198:201], v[126:129]
	v_mfma_f32_16x16x32_bf16 v[122:125], v[174:177], v[198:201], v[122:125]
	v_mfma_f32_16x16x32_bf16 v[110:113], v[166:169], v[206:209], v[110:113]
	v_mfma_f32_16x16x32_bf16 v[106:109], v[174:177], v[206:209], v[106:109]
	v_mfma_f32_16x16x32_bf16 v[94:97], v[166:169], v[214:217], v[94:97]
	v_mfma_f32_16x16x32_bf16 v[90:93], v[174:177], v[214:217], v[90:93]
	v_mfma_f32_16x16x32_bf16 v[78:81], v[166:169], v[222:225], v[78:81]
	v_mfma_f32_16x16x32_bf16 v[74:77], v[174:177], v[222:225], v[74:77]
	s_setprio 0
	s_setprio 1
	v_mfma_f32_16x16x32_bf16 v[118:121], v[178:181], v[194:197], v[118:121]
	v_mfma_f32_16x16x32_bf16 v[114:117], v[186:189], v[194:197], v[114:117]
	v_mfma_f32_16x16x32_bf16 v[102:105], v[178:181], v[202:205], v[102:105]
	v_mfma_f32_16x16x32_bf16 v[98:101], v[186:189], v[202:205], v[98:101]
	v_mfma_f32_16x16x32_bf16 v[86:89], v[178:181], v[210:213], v[86:89]
	v_mfma_f32_16x16x32_bf16 v[82:85], v[186:189], v[210:213], v[82:85]
	v_mfma_f32_16x16x32_bf16 v[70:73], v[178:181], v[218:221], v[70:73]
	v_mfma_f32_16x16x32_bf16 v[66:69], v[186:189], v[218:221], v[66:69]
	v_mfma_f32_16x16x32_bf16 v[118:121], v[182:185], v[198:201], v[118:121]
	v_mfma_f32_16x16x32_bf16 v[114:117], v[190:193], v[198:201], v[114:117]
	v_mfma_f32_16x16x32_bf16 v[102:105], v[182:185], v[206:209], v[102:105]
	v_mfma_f32_16x16x32_bf16 v[98:101], v[190:193], v[206:209], v[98:101]
	v_mfma_f32_16x16x32_bf16 v[86:89], v[182:185], v[214:217], v[86:89]
	v_mfma_f32_16x16x32_bf16 v[82:85], v[190:193], v[214:217], v[82:85]
	v_mfma_f32_16x16x32_bf16 v[70:73], v[182:185], v[222:225], v[70:73]
	v_mfma_f32_16x16x32_bf16 v[66:69], v[190:193], v[222:225], v[66:69]
	s_setprio 0
	s_barrier
	s_add_i32 s48, s39, s28
	v_lshl_add_u64 v[146:147], s[24:25], 0, v[134:135]
	s_mov_b32 m0, s48
	ds_read_b128 v[194:197], v161 offset:16384
	ds_read_b128 v[198:201], v161 offset:17408
	ds_read_b128 v[202:205], v161 offset:18432
	ds_read_b128 v[206:209], v161 offset:19456
	ds_read_b128 v[210:213], v161 offset:20480
	ds_read_b128 v[214:217], v161 offset:21504
	ds_read_b128 v[218:221], v161 offset:22528
	ds_read_b128 v[222:225], v161 offset:23552
	global_load_lds_dwordx4 v[146:147], off
	s_add_i32 m0, s48, 0x2000
	s_add_u32 s48, s24, 0x40000
	v_lshl_add_u64 v[150:151], s[24:25], 0, v[130:131]
	s_addc_u32 s49, s25, 0
	s_add_i32 s50, s40, s28
	global_load_lds_dwordx4 v[150:151], off
	v_lshl_add_u64 v[158:159], s[48:49], 0, v[134:135]
	s_mov_b32 m0, s50
	v_lshl_add_u64 v[226:227], s[26:27], 0, v[132:133]
	global_load_lds_dwordx4 v[158:159], off
	v_lshl_add_u64 v[158:159], s[48:49], 0, v[130:131]
	s_add_i32 m0, s50, 0x2000
	s_nop 0
	global_load_lds_dwordx4 v[158:159], off
	v_lshl_add_u64 v[158:159], s[26:27], 0, v[136:137]
	s_mov_b32 m0, s21
	s_nop 0
	global_load_lds_dwordx4 v[158:159], off
	s_mov_b32 m0, s31
	s_nop 0
	global_load_lds_dwordx4 v[226:227], off
	s_waitcnt vmcnt(8)
	s_waitcnt lgkmcnt(0)
	s_barrier
	s_setprio 1
	s_waitcnt lgkmcnt(0)
	v_mfma_f32_16x16x32_bf16 v[62:65], v[162:165], v[194:197], v[62:65]
	v_mfma_f32_16x16x32_bf16 v[58:61], v[170:173], v[194:197], v[58:61]
	v_mfma_f32_16x16x32_bf16 v[46:49], v[162:165], v[202:205], v[46:49]
	v_mfma_f32_16x16x32_bf16 v[42:45], v[170:173], v[202:205], v[42:45]
	v_mfma_f32_16x16x32_bf16 v[30:33], v[162:165], v[210:213], v[30:33]
	v_mfma_f32_16x16x32_bf16 v[26:29], v[170:173], v[210:213], v[26:29]
	v_mfma_f32_16x16x32_bf16 v[14:17], v[162:165], v[218:221], v[14:17]
	v_mfma_f32_16x16x32_bf16 v[10:13], v[170:173], v[218:221], v[10:13]
	v_mfma_f32_16x16x32_bf16 v[62:65], v[166:169], v[198:201], v[62:65]
	v_mfma_f32_16x16x32_bf16 v[58:61], v[174:177], v[198:201], v[58:61]
	v_mfma_f32_16x16x32_bf16 v[46:49], v[166:169], v[206:209], v[46:49]
	v_mfma_f32_16x16x32_bf16 v[42:45], v[174:177], v[206:209], v[42:45]
	v_mfma_f32_16x16x32_bf16 v[30:33], v[166:169], v[214:217], v[30:33]
	v_mfma_f32_16x16x32_bf16 v[26:29], v[174:177], v[214:217], v[26:29]
	v_mfma_f32_16x16x32_bf16 v[14:17], v[166:169], v[222:225], v[14:17]
	v_mfma_f32_16x16x32_bf16 v[10:13], v[174:177], v[222:225], v[10:13]
	s_setprio 0
	s_setprio 1
	v_mfma_f32_16x16x32_bf16 v[54:57], v[178:181], v[194:197], v[54:57]
	v_mfma_f32_16x16x32_bf16 v[50:53], v[186:189], v[194:197], v[50:53]
	v_mfma_f32_16x16x32_bf16 v[38:41], v[178:181], v[202:205], v[38:41]
	v_mfma_f32_16x16x32_bf16 v[34:37], v[186:189], v[202:205], v[34:37]
	v_mfma_f32_16x16x32_bf16 v[22:25], v[178:181], v[210:213], v[22:25]
	v_mfma_f32_16x16x32_bf16 v[18:21], v[186:189], v[210:213], v[18:21]
	v_mfma_f32_16x16x32_bf16 v[6:9], v[178:181], v[218:221], v[6:9]
	v_mfma_f32_16x16x32_bf16 v[2:5], v[186:189], v[218:221], v[2:5]
	v_mfma_f32_16x16x32_bf16 v[54:57], v[182:185], v[198:201], v[54:57]
	v_mfma_f32_16x16x32_bf16 v[50:53], v[190:193], v[198:201], v[50:53]
	v_mfma_f32_16x16x32_bf16 v[38:41], v[182:185], v[206:209], v[38:41]
	v_mfma_f32_16x16x32_bf16 v[34:37], v[190:193], v[206:209], v[34:37]
	v_mfma_f32_16x16x32_bf16 v[22:25], v[182:185], v[214:217], v[22:25]
	v_mfma_f32_16x16x32_bf16 v[18:21], v[190:193], v[214:217], v[18:21]
	v_mfma_f32_16x16x32_bf16 v[6:9], v[182:185], v[222:225], v[6:9]
	v_mfma_f32_16x16x32_bf16 v[2:5], v[190:193], v[222:225], v[2:5]
	s_setprio 0
	s_barrier
	s_add_i32 s48, 0, 0x18000
	v_add_u32_e32 v148, s48, v149
	s_add_i32 s49, 0, 0x1c000
	ds_read_b128 v[162:165], v148
	ds_read_b128 v[166:169], v148 offset:1024
	ds_read_b128 v[170:173], v148 offset:2048
	ds_read_b128 v[174:177], v148 offset:3072
	v_add_u32_e32 v148, s49, v149
	ds_read_b128 v[178:181], v148
	ds_read_b128 v[182:185], v148 offset:1024
	ds_read_b128 v[186:189], v148 offset:2048
	ds_read_b128 v[190:193], v148 offset:3072
	s_cmp_lg_u32 s47, 12
	s_cbranch_scc1 .Lg3_skip_ld
	v_lshl_add_u32 v230, s20, 8, v1
	v_lshlrev_b32_e32 v230, 2, v230
	global_load_dword v231, v230, s[64:65]
	global_load_dword v232, v230, s[64:65] offset:64
	global_load_dword v233, v230, s[64:65] offset:128
	global_load_dword v234, v230, s[64:65] offset:192
	global_load_dword v235, v230, s[64:65] offset:512
	global_load_dword v236, v230, s[64:65] offset:576
	global_load_dword v237, v230, s[64:65] offset:640
	global_load_dword v238, v230, s[64:65] offset:704
.Lg3_skip_ld:
	s_add_u32 s26, s26, 0x40000
	s_addc_u32 s27, s27, 0
	s_mov_b32 m0, s33
	v_lshl_add_u64 v[228:229], s[26:27], 0, v[136:137]
	ds_read_b128 v[194:197], v161 offset:32768
	ds_read_b128 v[198:201], v161 offset:33792
	ds_read_b128 v[202:205], v161 offset:34816
	ds_read_b128 v[206:209], v161 offset:35840
	ds_read_b128 v[210:213], v161 offset:36864
	ds_read_b128 v[214:217], v161 offset:37888
	ds_read_b128 v[218:221], v161 offset:38912
	ds_read_b128 v[222:225], v161 offset:39936
	global_load_lds_dwordx4 v[228:229], off
	v_lshl_add_u64 v[228:229], s[26:27], 0, v[132:133]
	s_mov_b32 m0, s34
	s_nop 0
	global_load_lds_dwordx4 v[228:229], off
	s_cmp_eq_u32 s47, 12
	s_cbranch_scc1 .Lg3_w1_last
	s_waitcnt vmcnt(8)
	s_branch .Lg3_w1_end

.Lg3_w1_end:
	s_waitcnt lgkmcnt(0)
	s_barrier
	s_setprio 1
	s_waitcnt lgkmcnt(0)
	v_mfma_f32_16x16x32_bf16 v[126:129], v[162:165], v[194:197], v[126:129]
	v_mfma_f32_16x16x32_bf16 v[122:125], v[170:173], v[194:197], v[122:125]
	v_mfma_f32_16x16x32_bf16 v[110:113], v[162:165], v[202:205], v[110:113]
	v_mfma_f32_16x16x32_bf16 v[106:109], v[170:173], v[202:205], v[106:109]
	v_mfma_f32_16x16x32_bf16 v[94:97], v[162:165], v[210:213], v[94:97]
	v_mfma_f32_16x16x32_bf16 v[90:93], v[170:173], v[210:213], v[90:93]
	v_mfma_f32_16x16x32_bf16 v[78:81], v[162:165], v[218:221], v[78:81]
	v_mfma_f32_16x16x32_bf16 v[74:77], v[170:173], v[218:221], v[74:77]
	v_mfma_f32_16x16x32_bf16 v[126:129], v[166:169], v[198:201], v[126:129]
	v_mfma_f32_16x16x32_bf16 v[122:125], v[174:177], v[198:201], v[122:125]
	v_mfma_f32_16x16x32_bf16 v[110:113], v[166:169], v[206:209], v[110:113]
	v_mfma_f32_16x16x32_bf16 v[106:109], v[174:177], v[206:209], v[106:109]
	v_mfma_f32_16x16x32_bf16 v[94:97], v[166:169], v[214:217], v[94:97]
	v_mfma_f32_16x16x32_bf16 v[90:93], v[174:177], v[214:217], v[90:93]
	v_mfma_f32_16x16x32_bf16 v[78:81], v[166:169], v[222:225], v[78:81]
	v_mfma_f32_16x16x32_bf16 v[74:77], v[174:177], v[222:225], v[74:77]
	s_setprio 0
	s_setprio 1
	v_mfma_f32_16x16x32_bf16 v[118:121], v[178:181], v[194:197], v[118:121]
	v_mfma_f32_16x16x32_bf16 v[114:117], v[186:189], v[194:197], v[114:117]
	v_mfma_f32_16x16x32_bf16 v[102:105], v[178:181], v[202:205], v[102:105]
	v_mfma_f32_16x16x32_bf16 v[98:101], v[186:189], v[202:205], v[98:101]
	v_mfma_f32_16x16x32_bf16 v[86:89], v[178:181], v[210:213], v[86:89]
	v_mfma_f32_16x16x32_bf16 v[82:85], v[186:189], v[210:213], v[82:85]
	v_mfma_f32_16x16x32_bf16 v[70:73], v[178:181], v[218:221], v[70:73]
	v_mfma_f32_16x16x32_bf16 v[66:69], v[186:189], v[218:221], v[66:69]
	v_mfma_f32_16x16x32_bf16 v[118:121], v[182:185], v[198:201], v[118:121]
	v_mfma_f32_16x16x32_bf16 v[114:117], v[190:193], v[198:201], v[114:117]
	v_mfma_f32_16x16x32_bf16 v[102:105], v[182:185], v[206:209], v[102:105]
	v_mfma_f32_16x16x32_bf16 v[98:101], v[190:193], v[206:209], v[98:101]
	v_mfma_f32_16x16x32_bf16 v[86:89], v[182:185], v[214:217], v[86:89]
	v_mfma_f32_16x16x32_bf16 v[82:85], v[190:193], v[214:217], v[82:85]
	v_mfma_f32_16x16x32_bf16 v[70:73], v[182:185], v[222:225], v[70:73]
	v_mfma_f32_16x16x32_bf16 v[66:69], v[190:193], v[222:225], v[66:69]
	s_setprio 0
	s_barrier
	s_add_i32 s26, s48, s28
	v_lshl_add_u64 v[146:147], v[146:147], 0, s[8:9]
	s_mov_b32 m0, s26
	ds_read_b128 v[194:197], v161 offset:49152
	ds_read_b128 v[198:201], v161 offset:50176
	ds_read_b128 v[202:205], v161 offset:51200
	ds_read_b128 v[206:209], v161 offset:52224
	ds_read_b128 v[210:213], v161 offset:53248
	ds_read_b128 v[214:217], v161 offset:54272
	ds_read_b128 v[218:221], v161 offset:55296
	ds_read_b128 v[222:225], v161 offset:56320
	global_load_lds_dwordx4 v[146:147], off
	s_add_i32 m0, s26, 0x2000
	s_add_u32 s24, s24, 0x40080
	v_lshl_add_u64 v[146:147], v[150:151], 0, s[8:9]
	s_addc_u32 s25, s25, 0
	s_add_i32 s26, s49, s28
	global_load_lds_dwordx4 v[146:147], off
	v_lshl_add_u64 v[146:147], s[24:25], 0, v[134:135]
	s_mov_b32 m0, s26
	s_nop 0
	global_load_lds_dwordx4 v[146:147], off
	v_lshl_add_u64 v[146:147], s[24:25], 0, v[130:131]
	s_add_i32 m0, s26, 0x2000
	s_nop 0
	global_load_lds_dwordx4 v[146:147], off
	v_lshl_add_u64 v[146:147], v[158:159], 0, s[8:9]
	s_mov_b32 m0, s36
	s_nop 0
	global_load_lds_dwordx4 v[146:147], off
	v_lshl_add_u64 v[146:147], v[226:227], 0, s[8:9]
	s_mov_b32 m0, s37
	s_nop 0
	global_load_lds_dwordx4 v[146:147], off
	s_cmp_eq_u32 s47, 12
	s_cbranch_scc1 .Lg3_w2_last
	s_waitcnt vmcnt(8)
	s_branch .Lg3_w2_end

.Lg3_w2_end:
	s_waitcnt lgkmcnt(0)
	s_barrier
	s_setprio 1
	s_waitcnt lgkmcnt(0)
	v_mfma_f32_16x16x32_bf16 v[62:65], v[162:165], v[194:197], v[62:65]
	v_mfma_f32_16x16x32_bf16 v[58:61], v[170:173], v[194:197], v[58:61]
	v_mfma_f32_16x16x32_bf16 v[46:49], v[162:165], v[202:205], v[46:49]
	v_mfma_f32_16x16x32_bf16 v[42:45], v[170:173], v[202:205], v[42:45]
	v_mfma_f32_16x16x32_bf16 v[30:33], v[162:165], v[210:213], v[30:33]
	v_mfma_f32_16x16x32_bf16 v[26:29], v[170:173], v[210:213], v[26:29]
	v_mfma_f32_16x16x32_bf16 v[14:17], v[162:165], v[218:221], v[14:17]
	v_mfma_f32_16x16x32_bf16 v[10:13], v[170:173], v[218:221], v[10:13]
	v_mfma_f32_16x16x32_bf16 v[62:65], v[166:169], v[198:201], v[62:65]
	v_mfma_f32_16x16x32_bf16 v[58:61], v[174:177], v[198:201], v[58:61]
	v_mfma_f32_16x16x32_bf16 v[46:49], v[166:169], v[206:209], v[46:49]
	v_mfma_f32_16x16x32_bf16 v[42:45], v[174:177], v[206:209], v[42:45]
	v_mfma_f32_16x16x32_bf16 v[30:33], v[166:169], v[214:217], v[30:33]
	v_mfma_f32_16x16x32_bf16 v[26:29], v[174:177], v[214:217], v[26:29]
	v_mfma_f32_16x16x32_bf16 v[14:17], v[166:169], v[222:225], v[14:17]
	v_mfma_f32_16x16x32_bf16 v[10:13], v[174:177], v[222:225], v[10:13]
	s_setprio 0
	s_setprio 1
	v_mfma_f32_16x16x32_bf16 v[54:57], v[178:181], v[194:197], v[54:57]
	v_mfma_f32_16x16x32_bf16 v[50:53], v[186:189], v[194:197], v[50:53]
	v_mfma_f32_16x16x32_bf16 v[38:41], v[178:181], v[202:205], v[38:41]
	v_mfma_f32_16x16x32_bf16 v[34:37], v[186:189], v[202:205], v[34:37]
	v_mfma_f32_16x16x32_bf16 v[22:25], v[178:181], v[210:213], v[22:25]
	v_mfma_f32_16x16x32_bf16 v[18:21], v[186:189], v[210:213], v[18:21]
	v_mfma_f32_16x16x32_bf16 v[6:9], v[178:181], v[218:221], v[6:9]
	v_mfma_f32_16x16x32_bf16 v[2:5], v[186:189], v[218:221], v[2:5]
	v_mfma_f32_16x16x32_bf16 v[54:57], v[182:185], v[198:201], v[54:57]
	v_mfma_f32_16x16x32_bf16 v[50:53], v[190:193], v[198:201], v[50:53]
	v_mfma_f32_16x16x32_bf16 v[38:41], v[182:185], v[206:209], v[38:41]
	v_mfma_f32_16x16x32_bf16 v[34:37], v[190:193], v[206:209], v[34:37]
	v_mfma_f32_16x16x32_bf16 v[22:25], v[182:185], v[214:217], v[22:25]
	v_mfma_f32_16x16x32_bf16 v[18:21], v[190:193], v[214:217], v[18:21]
	v_mfma_f32_16x16x32_bf16 v[6:9], v[182:185], v[222:225], v[6:9]
	v_mfma_f32_16x16x32_bf16 v[2:5], v[190:193], v[222:225], v[2:5]
	s_setprio 0
	s_barrier
	s_add_i32 s47, s47, 2
	s_add_u32 s22, s22, 0x100
	s_addc_u32 s23, s23, 0
	s_add_u32 s45, s45, 0x100
	s_addc_u32 s46, s46, 0
	s_cmp_gt_u32 s47, 13
	s_cbranch_scc0 .LBB0_1296
	s_and_b64 vcc, exec, s[10:11]
	s_cbranch_vccz .LBB0_1299
	s_barrier
.LBB0_1299:
	v_lshl_add_u32 v150, s20, 8, v1
	v_ashrrev_i32_e32 v151, 31, v150
	v_lshl_add_u64 v[170:171], v[150:151], 2, s[64:65]
	v_lshl_or_b32 v174, s42, 8, v153
	v_or_b32_e32 v176, 16, v150
	v_mov_b64_e32 v[146:147], s[68:69]
	v_or_b32_e32 v162, 32, v150
	v_or_b32_e32 v158, 48, v150
	v_ashrrev_i32_e32 v175, 31, v174
	v_ashrrev_i32_e32 v177, 31, v176
	v_add_u32_e32 v168, 0x80, v150
	v_add_u32_e32 v167, 0x90, v150
	v_add_u32_e32 v166, 0xa0, v150
	v_add_u32_e32 v165, 0xb0, v150
	v_mad_i64_i32 v[178:179], s[22:23], v150, s41, v[146:147]
	v_ashrrev_i32_e32 v163, 31, v162
	v_ashrrev_i32_e32 v159, 31, v158
	v_lshlrev_b64 v[150:151], 1, v[174:175]
	v_lshl_add_u64 v[174:175], v[176:177], 2, s[64:65]
	v_lshl_add_u64 v[180:181], v[162:163], 2, s[64:65]
	v_lshl_add_u64 v[182:183], v[158:159], 2, s[64:65]
	s_nop 0
	s_nop 0
	v_lshl_add_u64 v[178:179], v[178:179], 0, v[150:151]
	s_andn2_b64 vcc, exec, s[4:5]
	s_mov_b64 s[4:5], -1
	s_waitcnt vmcnt(8)
	v_mov_b32_e32 v148, v238
	v_mov_b32_e32 v160, v234
	v_mov_b32_e32 v164, v233
	v_mov_b32_e32 v174, v232
	v_mov_b32_e32 v152, v237
	v_mov_b32_e32 v154, v236
	v_mov_b32_e32 v156, v235
	v_mov_b32_e32 v172, v231
	v_pk_mul_f32 v[128:129], v[128:129], v[172:173] op_sel_hi:[1,0]
	v_pk_mul_f32 v[126:127], v[126:127], v[172:173] op_sel_hi:[1,0]
	v_pk_mul_f32 v[124:125], v[124:125], v[172:173] op_sel_hi:[1,0]
	v_pk_mul_f32 v[122:123], v[122:123], v[172:173] op_sel_hi:[1,0]
	v_pk_mul_f32 v[170:171], v[116:117], v[172:173] op_sel_hi:[1,0]
	v_mul_f32_e32 v116, 0xbfb8aa3b, v126
	v_mul_f32_e32 v117, 0xbfb8aa3b, v122
	v_mul_f32_e32 v122, 0xbfb8aa3b, v127
	v_mul_f32_e32 v123, 0xbfb8aa3b, v123
	v_mul_f32_e32 v126, 0xbfb8aa3b, v128
	v_mul_f32_e32 v124, 0xbfb8aa3b, v124
	v_mul_f32_e32 v127, 0xbfb8aa3b, v129
	v_mul_f32_e32 v125, 0xbfb8aa3b, v125
	v_exp_f32_e32 v116, v116
	v_exp_f32_e32 v117, v117
	v_exp_f32_e32 v122, v122
	v_exp_f32_e32 v123, v123
	v_exp_f32_e32 v126, v126
	v_exp_f32_e32 v124, v124
	v_exp_f32_e32 v127, v127
	v_exp_f32_e32 v125, v125
	v_pk_mul_f32 v[114:115], v[114:115], v[172:173] op_sel_hi:[1,0]
	v_add_f32_e32 v116, 1.0, v116
	v_mul_f32_e32 v114, 0xbfb8aa3b, v114
	v_mul_f32_e32 v115, 0xbfb8aa3b, v115
	v_exp_f32_e32 v114, v114
	v_exp_f32_e32 v115, v115
	v_add_f32_e32 v117, 1.0, v117
	v_add_f32_e32 v122, 1.0, v122
	v_add_f32_e32 v123, 1.0, v123
	v_add_f32_e32 v126, 1.0, v126
	v_add_f32_e32 v124, 1.0, v124
	v_add_f32_e32 v127, 1.0, v127
	v_add_f32_e32 v125, 1.0, v125
	v_rcp_f32_e32 v116, v116
	v_rcp_f32_e32 v117, v117
	v_rcp_f32_e32 v122, v122
	v_rcp_f32_e32 v123, v123
	v_rcp_f32_e32 v126, v126
	v_rcp_f32_e32 v124, v124
	v_rcp_f32_e32 v127, v127
	v_rcp_f32_e32 v125, v125
	v_pk_mul_f32 v[120:121], v[120:121], v[172:173] op_sel_hi:[1,0]
	v_add_f32_e32 v114, 1.0, v114
	v_mul_f32_e32 v120, 0xbfb8aa3b, v120
	v_add_f32_e32 v115, 1.0, v115
	v_mul_f32_e32 v128, 0xbfb8aa3b, v170
	v_exp_f32_e32 v120, v120
	v_rcp_f32_e32 v129, v114
	v_rcp_f32_e32 v159, v115
	v_cvt_pk_bf16_f32 v114, v116, v122
	v_cvt_pk_bf16_f32 v115, v126, v127
	v_cvt_pk_bf16_f32 v116, v117, v123
	v_cvt_pk_bf16_f32 v117, v124, v125
	v_pk_mul_f32 v[118:119], v[118:119], v[172:173] op_sel_hi:[1,0]
	v_exp_f32_e32 v128, v128
	global_store_dwordx4 v[178:179], v[114:117], off
	v_mul_f32_e32 v118, 0xbfb8aa3b, v118
	v_mul_f32_e32 v119, 0xbfb8aa3b, v119
	v_mul_f32_e32 v116, 0xbfb8aa3b, v121
	v_exp_f32_e32 v116, v116
	v_mul_f32_e32 v117, 0xbfb8aa3b, v171
	v_exp_f32_e32 v118, v118
	v_exp_f32_e32 v119, v119
	v_exp_f32_e32 v117, v117
	v_add_f32_e32 v114, 1.0, v120
	v_rcp_f32_e32 v115, v114
	v_add_f32_e32 v114, 1.0, v128
	v_rcp_f32_e32 v120, v114
	v_add_f32_e32 v114, 1.0, v116
	v_pk_mul_f32 v[106:107], v[106:107], v[174:175] op_sel_hi:[1,0]
	v_add_f32_e32 v118, 1.0, v118
	v_add_f32_e32 v119, 1.0, v119
	v_rcp_f32_e32 v116, v114
	v_add_f32_e32 v114, 1.0, v117
	v_pk_mul_f32 v[110:111], v[110:111], v[174:175] op_sel_hi:[1,0]
	v_mul_f32_e32 v106, 0xbfb8aa3b, v106
	v_rcp_f32_e32 v118, v118
	v_rcp_f32_e32 v119, v119
	v_rcp_f32_e32 v117, v114
	v_exp_f32_e32 v106, v106
	v_mul_f32_e32 v111, 0xbfb8aa3b, v111
	v_exp_f32_e32 v111, v111
	v_cvt_pk_bf16_f32 v114, v118, v119
	v_cvt_pk_bf16_f32 v115, v115, v116
	v_cvt_pk_bf16_f32 v116, v129, v159
	v_cvt_pk_bf16_f32 v117, v120, v117
	v_pk_mul_f32 v[112:113], v[112:113], v[174:175] op_sel_hi:[1,0]
	v_add_f32_e32 v106, 1.0, v106
	v_mul_f32_e32 v107, 0xbfb8aa3b, v107
	global_store_dwordx4 v[178:179], v[114:117], off offset:256
	v_exp_f32_e32 v107, v107
	v_pk_mul_f32 v[108:109], v[108:109], v[174:175] op_sel_hi:[1,0]
	v_rcp_f32_e32 v114, v106
	v_add_f32_e32 v106, 1.0, v111
	v_mul_f32_e32 v111, 0xbfb8aa3b, v112
	v_exp_f32_e32 v111, v111
	v_mul_f32_e32 v110, 0xbfb8aa3b, v110
	v_add_f32_e32 v107, 1.0, v107
	v_mul_f32_e32 v108, 0xbfb8aa3b, v108
	v_exp_f32_e32 v110, v110
	v_exp_f32_e32 v108, v108
	v_rcp_f32_e32 v112, v107
	v_add_f32_e32 v107, 1.0, v111
	v_mul_f32_e32 v111, 0xbfb8aa3b, v113
	v_mul_f32_e32 v109, 0xbfb8aa3b, v109
	v_exp_f32_e32 v111, v111
	v_exp_f32_e32 v109, v109
	v_add_f32_e32 v110, 1.0, v110
	v_add_f32_e32 v108, 1.0, v108
	v_pk_mul_f32 v[98:99], v[98:99], v[174:175] op_sel_hi:[1,0]
	v_rcp_f32_e32 v110, v110
	v_rcp_f32_e32 v106, v106
	v_rcp_f32_e32 v113, v108
	v_add_f32_e32 v108, 1.0, v111
	v_add_f32_e32 v109, 1.0, v109
	v_pk_mul_f32 v[102:103], v[102:103], v[174:175] op_sel_hi:[1,0]
	v_mul_f32_e32 v98, 0xbfb8aa3b, v98
	v_rcp_f32_e32 v107, v107
	v_rcp_f32_e32 v108, v108
	v_rcp_f32_e32 v109, v109
	v_exp_f32_e32 v98, v98
	v_mul_f32_e32 v103, 0xbfb8aa3b, v103
	v_exp_f32_e32 v103, v103
	v_cvt_pk_bf16_f32 v106, v110, v106
	v_mad_i64_i32 v[110:111], s[22:23], v176, s41, v[146:147]
	v_cvt_pk_bf16_f32 v107, v107, v108
	v_cvt_pk_bf16_f32 v108, v114, v112
	v_cvt_pk_bf16_f32 v109, v113, v109
	v_lshl_add_u64 v[110:111], v[110:111], 0, v[150:151]
	v_pk_mul_f32 v[104:105], v[104:105], v[174:175] op_sel_hi:[1,0]
	v_add_f32_e32 v98, 1.0, v98
	v_mul_f32_e32 v99, 0xbfb8aa3b, v99
	global_store_dwordx4 v[110:111], v[106:109], off
	v_exp_f32_e32 v99, v99
	v_pk_mul_f32 v[100:101], v[100:101], v[174:175] op_sel_hi:[1,0]
	v_rcp_f32_e32 v106, v98
	v_add_f32_e32 v98, 1.0, v103
	v_mul_f32_e32 v103, 0xbfb8aa3b, v104
	v_exp_f32_e32 v103, v103
	v_add_f32_e32 v99, 1.0, v99
	v_mul_f32_e32 v100, 0xbfb8aa3b, v100
	v_mul_f32_e32 v102, 0xbfb8aa3b, v102
	v_exp_f32_e32 v100, v100
	v_rcp_f32_e32 v104, v99
	v_add_f32_e32 v99, 1.0, v103
	v_mul_f32_e32 v103, 0xbfb8aa3b, v105
	v_mul_f32_e32 v101, 0xbfb8aa3b, v101
	v_exp_f32_e32 v102, v102
	v_exp_f32_e32 v103, v103
	v_exp_f32_e32 v101, v101
	v_add_f32_e32 v100, 1.0, v100
	v_pk_mul_f32 v[90:91], v[90:91], v[164:165] op_sel_hi:[1,0]
	v_add_f32_e32 v102, 1.0, v102
	v_rcp_f32_e32 v105, v100
	v_add_f32_e32 v100, 1.0, v103
	v_add_f32_e32 v101, 1.0, v101
	v_pk_mul_f32 v[94:95], v[94:95], v[164:165] op_sel_hi:[1,0]
	v_mul_f32_e32 v90, 0xbfb8aa3b, v90
	v_rcp_f32_e32 v102, v102
	v_rcp_f32_e32 v98, v98
	v_rcp_f32_e32 v99, v99
	v_rcp_f32_e32 v100, v100
	v_rcp_f32_e32 v101, v101
	v_exp_f32_e32 v90, v90
	v_mul_f32_e32 v95, 0xbfb8aa3b, v95
	v_exp_f32_e32 v95, v95
	v_cvt_pk_bf16_f32 v98, v102, v98
	v_cvt_pk_bf16_f32 v99, v99, v100
	v_cvt_pk_bf16_f32 v100, v106, v104
	v_cvt_pk_bf16_f32 v101, v105, v101
	v_pk_mul_f32 v[96:97], v[96:97], v[164:165] op_sel_hi:[1,0]
	v_add_f32_e32 v90, 1.0, v90
	v_mul_f32_e32 v91, 0xbfb8aa3b, v91
	global_store_dwordx4 v[110:111], v[98:101], off offset:256
	v_exp_f32_e32 v91, v91
	v_pk_mul_f32 v[92:93], v[92:93], v[164:165] op_sel_hi:[1,0]
	v_rcp_f32_e32 v98, v90
	v_add_f32_e32 v90, 1.0, v95
	v_mul_f32_e32 v95, 0xbfb8aa3b, v96
	v_exp_f32_e32 v95, v95
	v_mul_f32_e32 v94, 0xbfb8aa3b, v94
	v_add_f32_e32 v91, 1.0, v91
	v_mul_f32_e32 v92, 0xbfb8aa3b, v92
	v_exp_f32_e32 v94, v94
	v_exp_f32_e32 v92, v92
	v_rcp_f32_e32 v96, v91
	v_add_f32_e32 v91, 1.0, v95
	v_mul_f32_e32 v95, 0xbfb8aa3b, v97
	v_mul_f32_e32 v93, 0xbfb8aa3b, v93
	v_exp_f32_e32 v95, v95
	v_exp_f32_e32 v93, v93
	v_add_f32_e32 v94, 1.0, v94
	v_add_f32_e32 v92, 1.0, v92
	v_pk_mul_f32 v[82:83], v[82:83], v[164:165] op_sel_hi:[1,0]
	v_rcp_f32_e32 v94, v94
	v_rcp_f32_e32 v90, v90
	v_rcp_f32_e32 v97, v92
	v_add_f32_e32 v92, 1.0, v95
	v_add_f32_e32 v93, 1.0, v93
	v_pk_mul_f32 v[86:87], v[86:87], v[164:165] op_sel_hi:[1,0]
	v_mul_f32_e32 v82, 0xbfb8aa3b, v82
	v_rcp_f32_e32 v91, v91
	v_rcp_f32_e32 v92, v92
	v_rcp_f32_e32 v93, v93
	v_exp_f32_e32 v82, v82
	v_mul_f32_e32 v87, 0xbfb8aa3b, v87
	v_exp_f32_e32 v87, v87
	v_cvt_pk_bf16_f32 v90, v94, v90
	v_mad_i64_i32 v[94:95], s[22:23], v162, s41, v[146:147]
	v_cvt_pk_bf16_f32 v91, v91, v92
	v_cvt_pk_bf16_f32 v92, v98, v96
	v_cvt_pk_bf16_f32 v93, v97, v93
	v_lshl_add_u64 v[94:95], v[94:95], 0, v[150:151]
	v_pk_mul_f32 v[88:89], v[88:89], v[164:165] op_sel_hi:[1,0]
	v_add_f32_e32 v82, 1.0, v82
	v_mul_f32_e32 v83, 0xbfb8aa3b, v83
	global_store_dwordx4 v[94:95], v[90:93], off
	v_exp_f32_e32 v83, v83
	v_pk_mul_f32 v[84:85], v[84:85], v[164:165] op_sel_hi:[1,0]
	v_rcp_f32_e32 v90, v82
	v_add_f32_e32 v82, 1.0, v87
	v_mul_f32_e32 v87, 0xbfb8aa3b, v88
	v_exp_f32_e32 v87, v87
	v_add_f32_e32 v83, 1.0, v83
	v_mul_f32_e32 v84, 0xbfb8aa3b, v84
	v_mul_f32_e32 v86, 0xbfb8aa3b, v86
	v_exp_f32_e32 v84, v84
	v_rcp_f32_e32 v88, v83
	v_add_f32_e32 v83, 1.0, v87
	v_mul_f32_e32 v87, 0xbfb8aa3b, v89
	v_mul_f32_e32 v85, 0xbfb8aa3b, v85
	v_exp_f32_e32 v86, v86
	v_exp_f32_e32 v87, v87
	v_exp_f32_e32 v85, v85
	v_add_f32_e32 v84, 1.0, v84
	v_pk_mul_f32 v[74:75], v[74:75], v[160:161] op_sel_hi:[1,0]
	v_add_f32_e32 v86, 1.0, v86
	v_rcp_f32_e32 v89, v84
	v_add_f32_e32 v84, 1.0, v87
	v_add_f32_e32 v85, 1.0, v85
	v_pk_mul_f32 v[78:79], v[78:79], v[160:161] op_sel_hi:[1,0]
	v_mul_f32_e32 v74, 0xbfb8aa3b, v74
	v_rcp_f32_e32 v86, v86
	v_rcp_f32_e32 v82, v82
	v_rcp_f32_e32 v83, v83
	v_rcp_f32_e32 v84, v84
	v_rcp_f32_e32 v85, v85
	v_exp_f32_e32 v74, v74
	v_mul_f32_e32 v79, 0xbfb8aa3b, v79
	v_exp_f32_e32 v79, v79
	v_cvt_pk_bf16_f32 v82, v86, v82
	v_cvt_pk_bf16_f32 v83, v83, v84
	v_cvt_pk_bf16_f32 v84, v90, v88
	v_cvt_pk_bf16_f32 v85, v89, v85
	v_pk_mul_f32 v[80:81], v[80:81], v[160:161] op_sel_hi:[1,0]
	v_add_f32_e32 v74, 1.0, v74
	v_mul_f32_e32 v75, 0xbfb8aa3b, v75
	global_store_dwordx4 v[94:95], v[82:85], off offset:256
	v_exp_f32_e32 v75, v75
	v_pk_mul_f32 v[76:77], v[76:77], v[160:161] op_sel_hi:[1,0]
	v_rcp_f32_e32 v82, v74
	v_add_f32_e32 v74, 1.0, v79
	v_mul_f32_e32 v79, 0xbfb8aa3b, v80
	v_exp_f32_e32 v79, v79
	v_mul_f32_e32 v78, 0xbfb8aa3b, v78
	v_add_f32_e32 v75, 1.0, v75
	v_mul_f32_e32 v76, 0xbfb8aa3b, v76
	v_exp_f32_e32 v78, v78
	v_exp_f32_e32 v76, v76
	v_rcp_f32_e32 v80, v75
	v_add_f32_e32 v75, 1.0, v79
	v_mul_f32_e32 v79, 0xbfb8aa3b, v81
	v_mul_f32_e32 v77, 0xbfb8aa3b, v77
	v_exp_f32_e32 v79, v79
	v_exp_f32_e32 v77, v77
	v_add_f32_e32 v78, 1.0, v78
	v_add_f32_e32 v76, 1.0, v76
	v_pk_mul_f32 v[66:67], v[66:67], v[160:161] op_sel_hi:[1,0]
	v_rcp_f32_e32 v78, v78
	v_rcp_f32_e32 v74, v74
	v_rcp_f32_e32 v81, v76
	v_add_f32_e32 v76, 1.0, v79
	v_add_f32_e32 v77, 1.0, v77
	v_pk_mul_f32 v[70:71], v[70:71], v[160:161] op_sel_hi:[1,0]
	v_mul_f32_e32 v66, 0xbfb8aa3b, v66
	v_rcp_f32_e32 v75, v75
	v_rcp_f32_e32 v76, v76
	v_rcp_f32_e32 v77, v77
	v_exp_f32_e32 v66, v66
	v_mul_f32_e32 v71, 0xbfb8aa3b, v71
	v_exp_f32_e32 v71, v71
	v_cvt_pk_bf16_f32 v74, v78, v74
	v_mad_i64_i32 v[78:79], s[22:23], v158, s41, v[146:147]
	v_cvt_pk_bf16_f32 v75, v75, v76
	v_cvt_pk_bf16_f32 v76, v82, v80
	v_cvt_pk_bf16_f32 v77, v81, v77
	v_lshl_add_u64 v[78:79], v[78:79], 0, v[150:151]
	v_pk_mul_f32 v[72:73], v[72:73], v[160:161] op_sel_hi:[1,0]
	v_add_f32_e32 v66, 1.0, v66
	v_mul_f32_e32 v67, 0xbfb8aa3b, v67
	global_store_dwordx4 v[78:79], v[74:77], off
	v_exp_f32_e32 v67, v67
	v_pk_mul_f32 v[68:69], v[68:69], v[160:161] op_sel_hi:[1,0]
	v_rcp_f32_e32 v74, v66
	v_add_f32_e32 v66, 1.0, v71
	v_mul_f32_e32 v71, 0xbfb8aa3b, v72
	v_exp_f32_e32 v71, v71
	v_add_f32_e32 v67, 1.0, v67
	v_mul_f32_e32 v68, 0xbfb8aa3b, v68
	v_mul_f32_e32 v70, 0xbfb8aa3b, v70
	v_exp_f32_e32 v68, v68
	v_rcp_f32_e32 v72, v67
	v_add_f32_e32 v67, 1.0, v71
	v_mul_f32_e32 v71, 0xbfb8aa3b, v73
	v_mul_f32_e32 v69, 0xbfb8aa3b, v69
	v_exp_f32_e32 v70, v70
	v_exp_f32_e32 v71, v71
	v_exp_f32_e32 v69, v69
	v_add_f32_e32 v68, 1.0, v68
	v_pk_mul_f32 v[58:59], v[58:59], v[156:157] op_sel_hi:[1,0]
	v_add_f32_e32 v70, 1.0, v70
	v_rcp_f32_e32 v73, v68
	v_add_f32_e32 v68, 1.0, v71
	v_add_f32_e32 v69, 1.0, v69
	v_pk_mul_f32 v[62:63], v[62:63], v[156:157] op_sel_hi:[1,0]
	v_mul_f32_e32 v58, 0xbfb8aa3b, v58
	v_rcp_f32_e32 v70, v70
	v_rcp_f32_e32 v66, v66
	v_rcp_f32_e32 v67, v67
	v_rcp_f32_e32 v68, v68
	v_rcp_f32_e32 v69, v69
	v_exp_f32_e32 v58, v58
	v_mul_f32_e32 v63, 0xbfb8aa3b, v63
	v_exp_f32_e32 v63, v63
	v_cvt_pk_bf16_f32 v66, v70, v66
	v_cvt_pk_bf16_f32 v67, v67, v68
	v_cvt_pk_bf16_f32 v68, v74, v72
	v_cvt_pk_bf16_f32 v69, v73, v69
	v_pk_mul_f32 v[64:65], v[64:65], v[156:157] op_sel_hi:[1,0]
	v_add_f32_e32 v58, 1.0, v58
	v_mul_f32_e32 v59, 0xbfb8aa3b, v59
	global_store_dwordx4 v[78:79], v[66:69], off offset:256
	v_exp_f32_e32 v59, v59
	v_pk_mul_f32 v[60:61], v[60:61], v[156:157] op_sel_hi:[1,0]
	v_rcp_f32_e32 v66, v58
	v_add_f32_e32 v58, 1.0, v63
	v_mul_f32_e32 v63, 0xbfb8aa3b, v64
	v_exp_f32_e32 v63, v63
	v_mul_f32_e32 v62, 0xbfb8aa3b, v62
	v_add_f32_e32 v59, 1.0, v59
	v_mul_f32_e32 v60, 0xbfb8aa3b, v60
	v_exp_f32_e32 v62, v62
	v_exp_f32_e32 v60, v60
	v_rcp_f32_e32 v64, v59
	v_add_f32_e32 v59, 1.0, v63
	v_mul_f32_e32 v63, 0xbfb8aa3b, v65
	v_mul_f32_e32 v61, 0xbfb8aa3b, v61
	v_exp_f32_e32 v63, v63
	v_exp_f32_e32 v61, v61
	v_add_f32_e32 v62, 1.0, v62
	v_add_f32_e32 v60, 1.0, v60
	v_pk_mul_f32 v[50:51], v[50:51], v[156:157] op_sel_hi:[1,0]
	v_rcp_f32_e32 v62, v62
	v_rcp_f32_e32 v58, v58
	v_rcp_f32_e32 v65, v60
	v_add_f32_e32 v60, 1.0, v63
	v_add_f32_e32 v61, 1.0, v61
	v_pk_mul_f32 v[54:55], v[54:55], v[156:157] op_sel_hi:[1,0]
	v_mul_f32_e32 v50, 0xbfb8aa3b, v50
	v_rcp_f32_e32 v59, v59
	v_rcp_f32_e32 v60, v60
	v_rcp_f32_e32 v61, v61
	v_exp_f32_e32 v50, v50
	v_mul_f32_e32 v55, 0xbfb8aa3b, v55
	v_exp_f32_e32 v55, v55
	v_cvt_pk_bf16_f32 v58, v62, v58
	v_mad_i64_i32 v[62:63], s[22:23], v168, s41, v[146:147]
	v_cvt_pk_bf16_f32 v59, v59, v60
	v_cvt_pk_bf16_f32 v60, v66, v64
	v_cvt_pk_bf16_f32 v61, v65, v61
	v_lshl_add_u64 v[62:63], v[62:63], 0, v[150:151]
	v_pk_mul_f32 v[56:57], v[56:57], v[156:157] op_sel_hi:[1,0]
	v_add_f32_e32 v50, 1.0, v50
	v_mul_f32_e32 v51, 0xbfb8aa3b, v51
	global_store_dwordx4 v[62:63], v[58:61], off
	v_exp_f32_e32 v51, v51
	v_pk_mul_f32 v[52:53], v[52:53], v[156:157] op_sel_hi:[1,0]
	v_rcp_f32_e32 v58, v50
	v_add_f32_e32 v50, 1.0, v55
	v_mul_f32_e32 v55, 0xbfb8aa3b, v56
	v_exp_f32_e32 v55, v55
	v_add_f32_e32 v51, 1.0, v51
	v_mul_f32_e32 v52, 0xbfb8aa3b, v52
	v_mul_f32_e32 v54, 0xbfb8aa3b, v54
	v_exp_f32_e32 v52, v52
	v_rcp_f32_e32 v56, v51
	v_add_f32_e32 v51, 1.0, v55
	v_mul_f32_e32 v55, 0xbfb8aa3b, v57
	v_mul_f32_e32 v53, 0xbfb8aa3b, v53
	v_exp_f32_e32 v54, v54
	v_exp_f32_e32 v55, v55
	v_exp_f32_e32 v53, v53
	v_add_f32_e32 v52, 1.0, v52
	v_pk_mul_f32 v[42:43], v[42:43], v[154:155] op_sel_hi:[1,0]
	v_add_f32_e32 v54, 1.0, v54
	v_rcp_f32_e32 v57, v52
	v_add_f32_e32 v52, 1.0, v55
	v_add_f32_e32 v53, 1.0, v53
	v_pk_mul_f32 v[46:47], v[46:47], v[154:155] op_sel_hi:[1,0]
	v_mul_f32_e32 v42, 0xbfb8aa3b, v42
	v_rcp_f32_e32 v54, v54
	v_rcp_f32_e32 v50, v50
	v_rcp_f32_e32 v51, v51
	v_rcp_f32_e32 v52, v52
	v_rcp_f32_e32 v53, v53
	v_exp_f32_e32 v42, v42
	v_mul_f32_e32 v47, 0xbfb8aa3b, v47
	v_exp_f32_e32 v47, v47
	v_cvt_pk_bf16_f32 v50, v54, v50
	v_cvt_pk_bf16_f32 v51, v51, v52
	v_cvt_pk_bf16_f32 v52, v58, v56
	v_cvt_pk_bf16_f32 v53, v57, v53
	v_pk_mul_f32 v[48:49], v[48:49], v[154:155] op_sel_hi:[1,0]
	v_add_f32_e32 v42, 1.0, v42
	v_mul_f32_e32 v43, 0xbfb8aa3b, v43
	global_store_dwordx4 v[62:63], v[50:53], off offset:256
	v_exp_f32_e32 v43, v43
	v_pk_mul_f32 v[44:45], v[44:45], v[154:155] op_sel_hi:[1,0]
	v_rcp_f32_e32 v50, v42
	v_add_f32_e32 v42, 1.0, v47
	v_mul_f32_e32 v47, 0xbfb8aa3b, v48
	v_exp_f32_e32 v47, v47
	v_mul_f32_e32 v46, 0xbfb8aa3b, v46
	v_add_f32_e32 v43, 1.0, v43
	v_mul_f32_e32 v44, 0xbfb8aa3b, v44
	v_exp_f32_e32 v46, v46
	v_exp_f32_e32 v44, v44
	v_rcp_f32_e32 v48, v43
	v_add_f32_e32 v43, 1.0, v47
	v_mul_f32_e32 v47, 0xbfb8aa3b, v49
	v_mul_f32_e32 v45, 0xbfb8aa3b, v45
	v_exp_f32_e32 v47, v47
	v_exp_f32_e32 v45, v45
	v_add_f32_e32 v46, 1.0, v46
	v_add_f32_e32 v44, 1.0, v44
	v_pk_mul_f32 v[34:35], v[34:35], v[154:155] op_sel_hi:[1,0]
	v_rcp_f32_e32 v46, v46
	v_rcp_f32_e32 v42, v42
	v_rcp_f32_e32 v49, v44
	v_add_f32_e32 v44, 1.0, v47
	v_add_f32_e32 v45, 1.0, v45
	v_pk_mul_f32 v[38:39], v[38:39], v[154:155] op_sel_hi:[1,0]
	v_mul_f32_e32 v34, 0xbfb8aa3b, v34
	v_rcp_f32_e32 v43, v43
	v_rcp_f32_e32 v44, v44
	v_rcp_f32_e32 v45, v45
	v_exp_f32_e32 v34, v34
	v_mul_f32_e32 v39, 0xbfb8aa3b, v39
	v_exp_f32_e32 v39, v39
	v_cvt_pk_bf16_f32 v42, v46, v42
	v_mad_i64_i32 v[46:47], s[22:23], v167, s41, v[146:147]
	v_cvt_pk_bf16_f32 v43, v43, v44
	v_cvt_pk_bf16_f32 v44, v50, v48
	v_cvt_pk_bf16_f32 v45, v49, v45
	v_lshl_add_u64 v[46:47], v[46:47], 0, v[150:151]
	v_pk_mul_f32 v[40:41], v[40:41], v[154:155] op_sel_hi:[1,0]
	v_add_f32_e32 v34, 1.0, v34
	v_mul_f32_e32 v35, 0xbfb8aa3b, v35
	global_store_dwordx4 v[46:47], v[42:45], off
	v_exp_f32_e32 v35, v35
	v_pk_mul_f32 v[36:37], v[36:37], v[154:155] op_sel_hi:[1,0]
	v_rcp_f32_e32 v42, v34
	v_add_f32_e32 v34, 1.0, v39
	v_mul_f32_e32 v39, 0xbfb8aa3b, v40
	v_exp_f32_e32 v39, v39
	v_add_f32_e32 v35, 1.0, v35
	v_mul_f32_e32 v36, 0xbfb8aa3b, v36
	v_mul_f32_e32 v38, 0xbfb8aa3b, v38
	v_exp_f32_e32 v36, v36
	v_rcp_f32_e32 v40, v35
	v_add_f32_e32 v35, 1.0, v39
	v_mul_f32_e32 v39, 0xbfb8aa3b, v41
	v_mul_f32_e32 v37, 0xbfb8aa3b, v37
	v_exp_f32_e32 v38, v38
	v_exp_f32_e32 v39, v39
	v_exp_f32_e32 v37, v37
	v_add_f32_e32 v36, 1.0, v36
	v_pk_mul_f32 v[26:27], v[26:27], v[152:153] op_sel_hi:[1,0]
	v_add_f32_e32 v38, 1.0, v38
	v_rcp_f32_e32 v41, v36
	v_add_f32_e32 v36, 1.0, v39
	v_add_f32_e32 v37, 1.0, v37
	v_pk_mul_f32 v[30:31], v[30:31], v[152:153] op_sel_hi:[1,0]
	v_mul_f32_e32 v26, 0xbfb8aa3b, v26
	v_rcp_f32_e32 v38, v38
	v_rcp_f32_e32 v34, v34
	v_rcp_f32_e32 v35, v35
	v_rcp_f32_e32 v36, v36
	v_rcp_f32_e32 v37, v37
	v_exp_f32_e32 v26, v26
	v_mul_f32_e32 v31, 0xbfb8aa3b, v31
	v_exp_f32_e32 v31, v31
	v_cvt_pk_bf16_f32 v34, v38, v34
	v_cvt_pk_bf16_f32 v35, v35, v36
	v_cvt_pk_bf16_f32 v36, v42, v40
	v_cvt_pk_bf16_f32 v37, v41, v37
	v_pk_mul_f32 v[32:33], v[32:33], v[152:153] op_sel_hi:[1,0]
	v_add_f32_e32 v26, 1.0, v26
	v_mul_f32_e32 v27, 0xbfb8aa3b, v27
	global_store_dwordx4 v[46:47], v[34:37], off offset:256
	v_exp_f32_e32 v27, v27
	v_pk_mul_f32 v[28:29], v[28:29], v[152:153] op_sel_hi:[1,0]
	v_rcp_f32_e32 v34, v26
	v_add_f32_e32 v26, 1.0, v31
	v_mul_f32_e32 v31, 0xbfb8aa3b, v32
	v_exp_f32_e32 v31, v31
	v_mul_f32_e32 v30, 0xbfb8aa3b, v30
	v_add_f32_e32 v27, 1.0, v27
	v_mul_f32_e32 v28, 0xbfb8aa3b, v28
	v_exp_f32_e32 v30, v30
	v_exp_f32_e32 v28, v28
	v_rcp_f32_e32 v32, v27
	v_add_f32_e32 v27, 1.0, v31
	v_mul_f32_e32 v31, 0xbfb8aa3b, v33
	v_mul_f32_e32 v29, 0xbfb8aa3b, v29
	v_exp_f32_e32 v31, v31
	v_exp_f32_e32 v29, v29
	v_add_f32_e32 v30, 1.0, v30
	v_add_f32_e32 v28, 1.0, v28
	v_pk_mul_f32 v[18:19], v[18:19], v[152:153] op_sel_hi:[1,0]
	v_rcp_f32_e32 v30, v30
	v_rcp_f32_e32 v26, v26
	v_rcp_f32_e32 v33, v28
	v_add_f32_e32 v28, 1.0, v31
	v_add_f32_e32 v29, 1.0, v29
	v_pk_mul_f32 v[22:23], v[22:23], v[152:153] op_sel_hi:[1,0]
	v_mul_f32_e32 v18, 0xbfb8aa3b, v18
	v_rcp_f32_e32 v27, v27
	v_rcp_f32_e32 v28, v28
	v_rcp_f32_e32 v29, v29
	v_exp_f32_e32 v18, v18
	v_mul_f32_e32 v23, 0xbfb8aa3b, v23
	v_exp_f32_e32 v23, v23
	v_cvt_pk_bf16_f32 v26, v30, v26
	v_mad_i64_i32 v[30:31], s[22:23], v166, s41, v[146:147]
	v_cvt_pk_bf16_f32 v27, v27, v28
	v_cvt_pk_bf16_f32 v28, v34, v32
	v_cvt_pk_bf16_f32 v29, v33, v29
	v_lshl_add_u64 v[30:31], v[30:31], 0, v[150:151]
	v_pk_mul_f32 v[24:25], v[24:25], v[152:153] op_sel_hi:[1,0]
	v_add_f32_e32 v18, 1.0, v18
	v_mul_f32_e32 v19, 0xbfb8aa3b, v19
	global_store_dwordx4 v[30:31], v[26:29], off
	v_exp_f32_e32 v19, v19
	v_pk_mul_f32 v[20:21], v[20:21], v[152:153] op_sel_hi:[1,0]
	v_rcp_f32_e32 v26, v18
	v_add_f32_e32 v18, 1.0, v23
	v_mul_f32_e32 v23, 0xbfb8aa3b, v24
	v_exp_f32_e32 v23, v23
	v_add_f32_e32 v19, 1.0, v19
	v_mul_f32_e32 v20, 0xbfb8aa3b, v20
	v_mul_f32_e32 v22, 0xbfb8aa3b, v22
	v_exp_f32_e32 v20, v20
	v_rcp_f32_e32 v24, v19
	v_add_f32_e32 v19, 1.0, v23
	v_mul_f32_e32 v23, 0xbfb8aa3b, v25
	v_mul_f32_e32 v21, 0xbfb8aa3b, v21
	v_exp_f32_e32 v22, v22
	v_exp_f32_e32 v23, v23
	v_exp_f32_e32 v21, v21
	v_add_f32_e32 v20, 1.0, v20
	v_pk_mul_f32 v[10:11], v[10:11], v[148:149] op_sel_hi:[1,0]
	v_add_f32_e32 v22, 1.0, v22
	v_rcp_f32_e32 v25, v20
	v_add_f32_e32 v20, 1.0, v23
	v_add_f32_e32 v21, 1.0, v21
	v_pk_mul_f32 v[14:15], v[14:15], v[148:149] op_sel_hi:[1,0]
	v_mul_f32_e32 v10, 0xbfb8aa3b, v10
	v_rcp_f32_e32 v22, v22
	v_rcp_f32_e32 v18, v18
	v_rcp_f32_e32 v19, v19
	v_rcp_f32_e32 v20, v20
	v_rcp_f32_e32 v21, v21
	v_exp_f32_e32 v10, v10
	v_mul_f32_e32 v15, 0xbfb8aa3b, v15
	v_exp_f32_e32 v15, v15
	v_cvt_pk_bf16_f32 v18, v22, v18
	v_cvt_pk_bf16_f32 v19, v19, v20
	v_cvt_pk_bf16_f32 v20, v26, v24
	v_cvt_pk_bf16_f32 v21, v25, v21
	v_pk_mul_f32 v[16:17], v[16:17], v[148:149] op_sel_hi:[1,0]
	v_add_f32_e32 v10, 1.0, v10
	v_mul_f32_e32 v11, 0xbfb8aa3b, v11
	global_store_dwordx4 v[30:31], v[18:21], off offset:256
	v_exp_f32_e32 v11, v11
	v_pk_mul_f32 v[12:13], v[12:13], v[148:149] op_sel_hi:[1,0]
	v_rcp_f32_e32 v18, v10
	v_add_f32_e32 v10, 1.0, v15
	v_mul_f32_e32 v15, 0xbfb8aa3b, v16
	v_exp_f32_e32 v15, v15
	v_mul_f32_e32 v14, 0xbfb8aa3b, v14
	v_add_f32_e32 v11, 1.0, v11
	v_mul_f32_e32 v12, 0xbfb8aa3b, v12
	v_exp_f32_e32 v14, v14
	v_exp_f32_e32 v12, v12
	v_rcp_f32_e32 v16, v11
	v_add_f32_e32 v11, 1.0, v15
	v_mul_f32_e32 v15, 0xbfb8aa3b, v17
	v_mul_f32_e32 v13, 0xbfb8aa3b, v13
	v_exp_f32_e32 v15, v15
	v_exp_f32_e32 v13, v13
	v_add_f32_e32 v14, 1.0, v14
	v_add_f32_e32 v12, 1.0, v12
	v_pk_mul_f32 v[2:3], v[2:3], v[148:149] op_sel_hi:[1,0]
	v_rcp_f32_e32 v14, v14
	v_rcp_f32_e32 v10, v10
	v_rcp_f32_e32 v17, v12
	v_add_f32_e32 v12, 1.0, v15
	v_add_f32_e32 v13, 1.0, v13
	v_pk_mul_f32 v[6:7], v[6:7], v[148:149] op_sel_hi:[1,0]
	v_mul_f32_e32 v2, 0xbfb8aa3b, v2
	v_rcp_f32_e32 v11, v11
	v_rcp_f32_e32 v12, v12
	v_rcp_f32_e32 v13, v13
	v_exp_f32_e32 v2, v2
	v_mul_f32_e32 v7, 0xbfb8aa3b, v7
	v_exp_f32_e32 v7, v7
	v_cvt_pk_bf16_f32 v10, v14, v10
	v_mad_i64_i32 v[14:15], s[22:23], v165, s41, v[146:147]
	v_cvt_pk_bf16_f32 v11, v11, v12
	v_cvt_pk_bf16_f32 v12, v18, v16
	v_cvt_pk_bf16_f32 v13, v17, v13
	v_lshl_add_u64 v[14:15], v[14:15], 0, v[150:151]
	v_pk_mul_f32 v[8:9], v[8:9], v[148:149] op_sel_hi:[1,0]
	v_add_f32_e32 v2, 1.0, v2
	v_mul_f32_e32 v3, 0xbfb8aa3b, v3
	global_store_dwordx4 v[14:15], v[10:13], off
	v_exp_f32_e32 v3, v3
	v_pk_mul_f32 v[4:5], v[4:5], v[148:149] op_sel_hi:[1,0]
	v_rcp_f32_e32 v10, v2
	v_add_f32_e32 v2, 1.0, v7
	v_mul_f32_e32 v7, 0xbfb8aa3b, v8
	v_exp_f32_e32 v7, v7
	v_add_f32_e32 v3, 1.0, v3
	v_mul_f32_e32 v4, 0xbfb8aa3b, v4
	v_mul_f32_e32 v6, 0xbfb8aa3b, v6
	v_exp_f32_e32 v4, v4
	v_rcp_f32_e32 v8, v3
	v_add_f32_e32 v3, 1.0, v7
	v_mul_f32_e32 v7, 0xbfb8aa3b, v9
	v_mul_f32_e32 v5, 0xbfb8aa3b, v5
	v_exp_f32_e32 v6, v6
	v_exp_f32_e32 v7, v7
	v_exp_f32_e32 v5, v5
	v_add_f32_e32 v4, 1.0, v4
	v_add_f32_e32 v6, 1.0, v6
	v_rcp_f32_e32 v9, v4
	v_add_f32_e32 v4, 1.0, v7
	v_add_f32_e32 v5, 1.0, v5
	v_rcp_f32_e32 v6, v6
	v_rcp_f32_e32 v2, v2
	v_rcp_f32_e32 v3, v3
	v_rcp_f32_e32 v4, v4
	v_rcp_f32_e32 v5, v5
	v_cvt_pk_bf16_f32 v2, v6, v2
	v_cvt_pk_bf16_f32 v3, v3, v4
	v_cvt_pk_bf16_f32 v4, v10, v8
	v_cvt_pk_bf16_f32 v5, v9, v5
	global_store_dwordx4 v[14:15], v[2:5], off offset:256
	s_cbranch_vccnz .LBB0_1292
	s_andn2_b64 vcc, exec, s[6:7]
	s_cbranch_vccnz .LBB0_1291
	s_barrier
	s_branch .LBB0_1291
